# merge epilogue: redundant canonicalising v_max(x,x) before fmaxf(next gate, 1e-30) folded into the real max
# speedup vs baseline: 1.0176x; 1.0104x over previous
; __device__ __forceinline__ void unpack8(const u32x4 w, float (&f)[8]) { f[0] = bflo(w.x); f[1] = bfhi(w.x); f[2] = bflo(w.y); f[3] = bfhi(w.y); f[4] = bflo(w.z); f[5] = bfhi(w.z); f[6] = bflo(w.w); f[7] = bfhi(w.w); }
; __device__ __forceinline__ u32x4 pack8(const float (&f)[8]) { u32x4 w; w.x = cvt_pk_bf16(f[0], f[1]); w.y = cvt_pk_bf16(f[2], f[3]); w.z = cvt_pk_bf16(f[4], f[5]); w.w = cvt_pk_bf16(f[6], f[7]); return w; }
;     __device__ __forceinline__ void operator()(f32x4 (&acc)[2][2][4][2], const Unit& u, int wr, int wc, int fr, int fq) const {
;     ...
;             for (int m = 0; m < 4; ++m)
; #pragma unroll
;                 for (int bj = 0; bj < 2; ++bj) { const size_t row = (size_t)(row0 + ai * HALF + m * 16); const int col = col0 + bj * HALF;
;                     float gf[8], nf[8], v[8]; unpack8(gw[m][bj], gf); unpack8(gn[m][bj], nf);
; #pragma unroll
;                     for (int j = 0; j < 4; ++j) { v[j] = gf[j] * acc[ai][bj][m][0][j]; v[4 + j] = gf[4 + j] * acc[ai][bj][m][1][j]; }
;                     if (last) { *(u32x4*)(MG + row * 1024 + col) = pack8(v); acc[ai][bj][m][0] = (f32x4){0.f, 0.f, 0.f, 0.f}; acc[ai][bj][m][1] = (f32x4){0.f, 0.f, 0.f, 0.f}; }
;                     else {
; #pragma unroll
;                         for (int j = 0; j < 4; ++j) { acc[ai][bj][m][0][j] = v[j] * __builtin_amdgcn_rcpf(fmaxf(nf[j], 1e-30f)); acc[ai][bj][m][1][j] = v[4 + j] * __builtin_amdgcn_rcpf(fmaxf(nf[4 + j], 1e-30f)); } }
.LBB0_281:
	s_waitcnt vmcnt(0)
	v_lshlrev_b32_e32 v224, 16, v190
	v_and_b32_e32 v225, 0xffff0000, v190
	v_pk_mul_f32 v[226:227], v[126:127], v[224:225]
	v_lshlrev_b32_e32 v126, 16, v192
	v_and_b32_e32 v127, 0xffff0000, v192
	v_pk_mul_f32 v[224:225], v[122:123], v[126:127]
	v_lshlrev_b32_e32 v122, 16, v191
	v_and_b32_e32 v123, 0xffff0000, v191
	v_pk_mul_f32 v[190:191], v[128:129], v[122:123]
	v_lshlrev_b32_e32 v122, 16, v193
	v_and_b32_e32 v123, 0xffff0000, v193
	v_pk_mul_f32 v[192:193], v[124:125], v[122:123]
	s_and_b64 vcc, exec, s[38:39]
	s_mov_b64 s[30:31], -1
	s_cbranch_vccnz .LBB0_283
	v_lshlrev_b32_e32 v126, 16, v187
	v_lshlrev_b32_e32 v129, 16, v189
	v_max_f32_e32 v126, 0xda24260, v126
	v_rcp_f32_e32 v128, v126
	v_and_b32_e32 v127, 0xffff0000, v187
	v_max_f32_e32 v126, 0xda24260, v129
	v_lshlrev_b32_e32 v122, 16, v186
	v_and_b32_e32 v123, 0xffff0000, v186
	v_rcp_f32_e32 v186, v126
	v_lshlrev_b32_e32 v124, 16, v188
	v_and_b32_e32 v125, 0xffff0000, v188
	v_and_b32_e32 v187, 0xffff0000, v189
	v_max_f32_e32 v126, 0xda24260, v127
	v_rcp_f32_e32 v129, v126
	v_max_f32_e32 v122, 0xda24260, v122
	v_max_f32_e32 v124, 0xda24260, v124
	v_max_f32_e32 v123, 0xda24260, v123
	v_max_f32_e32 v125, 0xda24260, v125
	v_max_f32_e32 v126, 0xda24260, v187
	v_rcp_f32_e32 v122, v122
	v_rcp_f32_e32 v124, v124
	v_rcp_f32_e32 v123, v123
	v_rcp_f32_e32 v125, v125
	v_rcp_f32_e32 v187, v126
	v_pk_mul_f32 v[128:129], v[190:191], v[128:129]
	v_pk_mul_f32 v[126:127], v[226:227], v[122:123]
	v_pk_mul_f32 v[122:123], v[224:225], v[124:125]
	v_pk_mul_f32 v[124:125], v[192:193], v[186:187]
	s_mov_b64 s[30:31], 0

; __device__ __forceinline__ void unpack8(const u32x4 w, float (&f)[8]) { f[0] = bflo(w.x); f[1] = bfhi(w.x); f[2] = bflo(w.y); f[3] = bfhi(w.y); f[4] = bflo(w.z); f[5] = bfhi(w.z); f[6] = bflo(w.w); f[7] = bfhi(w.w); }
; __device__ __forceinline__ u32x4 pack8(const float (&f)[8]) { u32x4 w; w.x = cvt_pk_bf16(f[0], f[1]); w.y = cvt_pk_bf16(f[2], f[3]); w.z = cvt_pk_bf16(f[4], f[5]); w.w = cvt_pk_bf16(f[6], f[7]); return w; }
;     __device__ __forceinline__ void operator()(f32x4 (&acc)[2][2][4][2], const Unit& u, int wr, int wc, int fr, int fq) const {
;     ...
;             for (int m = 0; m < 4; ++m)
; #pragma unroll
;                 for (int bj = 0; bj < 2; ++bj) { const size_t row = (size_t)(row0 + ai * HALF + m * 16); const int col = col0 + bj * HALF;
;                     float gf[8], nf[8], v[8]; unpack8(gw[m][bj], gf); unpack8(gn[m][bj], nf);
; #pragma unroll
;                     for (int j = 0; j < 4; ++j) { v[j] = gf[j] * acc[ai][bj][m][0][j]; v[4 + j] = gf[4 + j] * acc[ai][bj][m][1][j]; }
;                     if (last) { *(u32x4*)(MG + row * 1024 + col) = pack8(v); acc[ai][bj][m][0] = (f32x4){0.f, 0.f, 0.f, 0.f}; acc[ai][bj][m][1] = (f32x4){0.f, 0.f, 0.f, 0.f}; }
;                     else {
; #pragma unroll
;                         for (int j = 0; j < 4; ++j) { acc[ai][bj][m][0][j] = v[j] * __builtin_amdgcn_rcpf(fmaxf(nf[j], 1e-30f)); acc[ai][bj][m][1][j] = v[4 + j] * __builtin_amdgcn_rcpf(fmaxf(nf[4 + j], 1e-30f)); } }
.LBB0_285:
	v_lshlrev_b32_e32 v188, 16, v182
	v_and_b32_e32 v189, 0xffff0000, v182
	v_pk_mul_f32 v[190:191], v[94:95], v[188:189]
	v_lshlrev_b32_e32 v94, 16, v184
	v_and_b32_e32 v95, 0xffff0000, v184
	v_pk_mul_f32 v[188:189], v[90:91], v[94:95]
	v_lshlrev_b32_e32 v90, 16, v183
	v_and_b32_e32 v91, 0xffff0000, v183
	v_pk_mul_f32 v[182:183], v[96:97], v[90:91]
	v_lshlrev_b32_e32 v90, 16, v185
	v_and_b32_e32 v91, 0xffff0000, v185
	v_pk_mul_f32 v[184:185], v[92:93], v[90:91]
	s_and_b64 vcc, exec, s[38:39]
	s_mov_b64 s[30:31], -1
	s_cbranch_vccnz .LBB0_287
	v_lshlrev_b32_e32 v94, 16, v179
	v_lshlrev_b32_e32 v97, 16, v181
	v_max_f32_e32 v94, 0xda24260, v94
	v_rcp_f32_e32 v96, v94
	v_and_b32_e32 v95, 0xffff0000, v179
	v_max_f32_e32 v94, 0xda24260, v97
	v_lshlrev_b32_e32 v90, 16, v178
	v_and_b32_e32 v91, 0xffff0000, v178
	v_rcp_f32_e32 v178, v94
	v_lshlrev_b32_e32 v92, 16, v180
	v_and_b32_e32 v93, 0xffff0000, v180
	v_and_b32_e32 v179, 0xffff0000, v181
	v_max_f32_e32 v94, 0xda24260, v95
	v_rcp_f32_e32 v97, v94
	v_max_f32_e32 v90, 0xda24260, v90
	v_max_f32_e32 v92, 0xda24260, v92
	v_max_f32_e32 v91, 0xda24260, v91
	v_max_f32_e32 v93, 0xda24260, v93
	v_max_f32_e32 v94, 0xda24260, v179
	v_rcp_f32_e32 v90, v90
	v_rcp_f32_e32 v92, v92
	v_rcp_f32_e32 v91, v91
	v_rcp_f32_e32 v93, v93
	v_rcp_f32_e32 v179, v94
	v_pk_mul_f32 v[96:97], v[182:183], v[96:97]
	v_pk_mul_f32 v[94:95], v[190:191], v[90:91]
	v_pk_mul_f32 v[90:91], v[188:189], v[92:93]
	v_pk_mul_f32 v[92:93], v[184:185], v[178:179]
	s_mov_b64 s[30:31], 0

; __device__ __forceinline__ void unpack8(const u32x4 w, float (&f)[8]) { f[0] = bflo(w.x); f[1] = bfhi(w.x); f[2] = bflo(w.y); f[3] = bfhi(w.y); f[4] = bflo(w.z); f[5] = bfhi(w.z); f[6] = bflo(w.w); f[7] = bfhi(w.w); }
; __device__ __forceinline__ u32x4 pack8(const float (&f)[8]) { u32x4 w; w.x = cvt_pk_bf16(f[0], f[1]); w.y = cvt_pk_bf16(f[2], f[3]); w.z = cvt_pk_bf16(f[4], f[5]); w.w = cvt_pk_bf16(f[6], f[7]); return w; }
;     __device__ __forceinline__ void operator()(f32x4 (&acc)[2][2][4][2], const Unit& u, int wr, int wc, int fr, int fq) const {
;     ...
;             for (int m = 0; m < 4; ++m)
; #pragma unroll
;                 for (int bj = 0; bj < 2; ++bj) { const size_t row = (size_t)(row0 + ai * HALF + m * 16); const int col = col0 + bj * HALF;
;                     float gf[8], nf[8], v[8]; unpack8(gw[m][bj], gf); unpack8(gn[m][bj], nf);
; #pragma unroll
;                     for (int j = 0; j < 4; ++j) { v[j] = gf[j] * acc[ai][bj][m][0][j]; v[4 + j] = gf[4 + j] * acc[ai][bj][m][1][j]; }
;                     if (last) { *(u32x4*)(MG + row * 1024 + col) = pack8(v); acc[ai][bj][m][0] = (f32x4){0.f, 0.f, 0.f, 0.f}; acc[ai][bj][m][1] = (f32x4){0.f, 0.f, 0.f, 0.f}; }
;                     else {
; #pragma unroll
;                         for (int j = 0; j < 4; ++j) { acc[ai][bj][m][0][j] = v[j] * __builtin_amdgcn_rcpf(fmaxf(nf[j], 1e-30f)); acc[ai][bj][m][1][j] = v[4 + j] * __builtin_amdgcn_rcpf(fmaxf(nf[4 + j], 1e-30f)); } }
.LBB0_289:
	v_lshlrev_b32_e32 v178, 16, v174
	v_and_b32_e32 v179, 0xffff0000, v174
	v_pk_mul_f32 v[180:181], v[118:119], v[178:179]
	v_lshlrev_b32_e32 v118, 16, v176
	v_and_b32_e32 v119, 0xffff0000, v176
	v_pk_mul_f32 v[178:179], v[114:115], v[118:119]
	v_lshlrev_b32_e32 v114, 16, v175
	v_and_b32_e32 v115, 0xffff0000, v175
	v_pk_mul_f32 v[174:175], v[120:121], v[114:115]
	v_lshlrev_b32_e32 v114, 16, v177
	v_and_b32_e32 v115, 0xffff0000, v177
	v_pk_mul_f32 v[176:177], v[116:117], v[114:115]
	s_and_b64 vcc, exec, s[38:39]
	s_mov_b64 s[30:31], -1
	s_cbranch_vccnz .LBB0_291
	v_lshlrev_b32_e32 v118, 16, v171
	v_lshlrev_b32_e32 v121, 16, v173
	v_max_f32_e32 v118, 0xda24260, v118
	v_rcp_f32_e32 v120, v118
	v_and_b32_e32 v119, 0xffff0000, v171
	v_max_f32_e32 v118, 0xda24260, v121
	v_lshlrev_b32_e32 v114, 16, v170
	v_and_b32_e32 v115, 0xffff0000, v170
	v_rcp_f32_e32 v170, v118
	v_lshlrev_b32_e32 v116, 16, v172
	v_and_b32_e32 v117, 0xffff0000, v172
	v_and_b32_e32 v171, 0xffff0000, v173
	v_max_f32_e32 v118, 0xda24260, v119
	v_rcp_f32_e32 v121, v118
	v_max_f32_e32 v114, 0xda24260, v114
	v_max_f32_e32 v116, 0xda24260, v116
	v_max_f32_e32 v115, 0xda24260, v115
	v_max_f32_e32 v117, 0xda24260, v117
	v_max_f32_e32 v118, 0xda24260, v171
	v_rcp_f32_e32 v114, v114
	v_rcp_f32_e32 v116, v116
	v_rcp_f32_e32 v115, v115
	v_rcp_f32_e32 v117, v117
	v_rcp_f32_e32 v171, v118
	v_pk_mul_f32 v[120:121], v[174:175], v[120:121]
	v_pk_mul_f32 v[118:119], v[180:181], v[114:115]
	v_pk_mul_f32 v[114:115], v[178:179], v[116:117]
	v_pk_mul_f32 v[116:117], v[176:177], v[170:171]
	s_mov_b64 s[30:31], 0

; __device__ __forceinline__ void unpack8(const u32x4 w, float (&f)[8]) { f[0] = bflo(w.x); f[1] = bfhi(w.x); f[2] = bflo(w.y); f[3] = bfhi(w.y); f[4] = bflo(w.z); f[5] = bfhi(w.z); f[6] = bflo(w.w); f[7] = bfhi(w.w); }
; __device__ __forceinline__ u32x4 pack8(const float (&f)[8]) { u32x4 w; w.x = cvt_pk_bf16(f[0], f[1]); w.y = cvt_pk_bf16(f[2], f[3]); w.z = cvt_pk_bf16(f[4], f[5]); w.w = cvt_pk_bf16(f[6], f[7]); return w; }
;     __device__ __forceinline__ void operator()(f32x4 (&acc)[2][2][4][2], const Unit& u, int wr, int wc, int fr, int fq) const {
;     ...
;             for (int m = 0; m < 4; ++m)
; #pragma unroll
;                 for (int bj = 0; bj < 2; ++bj) { const size_t row = (size_t)(row0 + ai * HALF + m * 16); const int col = col0 + bj * HALF;
;                     float gf[8], nf[8], v[8]; unpack8(gw[m][bj], gf); unpack8(gn[m][bj], nf);
; #pragma unroll
;                     for (int j = 0; j < 4; ++j) { v[j] = gf[j] * acc[ai][bj][m][0][j]; v[4 + j] = gf[4 + j] * acc[ai][bj][m][1][j]; }
;                     if (last) { *(u32x4*)(MG + row * 1024 + col) = pack8(v); acc[ai][bj][m][0] = (f32x4){0.f, 0.f, 0.f, 0.f}; acc[ai][bj][m][1] = (f32x4){0.f, 0.f, 0.f, 0.f}; }
;                     else {
; #pragma unroll
;                         for (int j = 0; j < 4; ++j) { acc[ai][bj][m][0][j] = v[j] * __builtin_amdgcn_rcpf(fmaxf(nf[j], 1e-30f)); acc[ai][bj][m][1][j] = v[4 + j] * __builtin_amdgcn_rcpf(fmaxf(nf[4 + j], 1e-30f)); } }
.LBB0_293:
	v_lshlrev_b32_e32 v172, 16, v166
	v_and_b32_e32 v173, 0xffff0000, v166
	v_pk_mul_f32 v[174:175], v[86:87], v[172:173]
	v_lshlrev_b32_e32 v86, 16, v168
	v_and_b32_e32 v87, 0xffff0000, v168
	v_pk_mul_f32 v[172:173], v[82:83], v[86:87]
	v_lshlrev_b32_e32 v82, 16, v167
	v_and_b32_e32 v83, 0xffff0000, v167
	v_pk_mul_f32 v[166:167], v[88:89], v[82:83]
	v_lshlrev_b32_e32 v82, 16, v169
	v_and_b32_e32 v83, 0xffff0000, v169
	v_pk_mul_f32 v[168:169], v[84:85], v[82:83]
	s_and_b64 vcc, exec, s[38:39]
	s_mov_b64 s[30:31], -1
	s_cbranch_vccnz .LBB0_295
	v_lshlrev_b32_e32 v86, 16, v163
	v_lshlrev_b32_e32 v89, 16, v165
	v_max_f32_e32 v86, 0xda24260, v86
	v_rcp_f32_e32 v88, v86
	v_and_b32_e32 v87, 0xffff0000, v163
	v_max_f32_e32 v86, 0xda24260, v89
	v_lshlrev_b32_e32 v82, 16, v162
	v_and_b32_e32 v83, 0xffff0000, v162
	v_rcp_f32_e32 v162, v86
	v_lshlrev_b32_e32 v84, 16, v164
	v_and_b32_e32 v85, 0xffff0000, v164
	v_and_b32_e32 v163, 0xffff0000, v165
	v_max_f32_e32 v86, 0xda24260, v87
	v_rcp_f32_e32 v89, v86
	v_max_f32_e32 v82, 0xda24260, v82
	v_max_f32_e32 v84, 0xda24260, v84
	v_max_f32_e32 v83, 0xda24260, v83
	v_max_f32_e32 v85, 0xda24260, v85
	v_max_f32_e32 v86, 0xda24260, v163
	v_rcp_f32_e32 v82, v82
	v_rcp_f32_e32 v84, v84
	v_rcp_f32_e32 v83, v83
	v_rcp_f32_e32 v85, v85
	v_rcp_f32_e32 v163, v86
	v_pk_mul_f32 v[88:89], v[166:167], v[88:89]
	v_pk_mul_f32 v[86:87], v[174:175], v[82:83]
	v_pk_mul_f32 v[82:83], v[172:173], v[84:85]
	v_pk_mul_f32 v[84:85], v[168:169], v[162:163]
	s_mov_b64 s[30:31], 0

; __device__ __forceinline__ void unpack8(const u32x4 w, float (&f)[8]) { f[0] = bflo(w.x); f[1] = bfhi(w.x); f[2] = bflo(w.y); f[3] = bfhi(w.y); f[4] = bflo(w.z); f[5] = bfhi(w.z); f[6] = bflo(w.w); f[7] = bfhi(w.w); }
; __device__ __forceinline__ u32x4 pack8(const float (&f)[8]) { u32x4 w; w.x = cvt_pk_bf16(f[0], f[1]); w.y = cvt_pk_bf16(f[2], f[3]); w.z = cvt_pk_bf16(f[4], f[5]); w.w = cvt_pk_bf16(f[6], f[7]); return w; }
;     __device__ __forceinline__ void operator()(f32x4 (&acc)[2][2][4][2], const Unit& u, int wr, int wc, int fr, int fq) const {
;     ...
;             for (int m = 0; m < 4; ++m)
; #pragma unroll
;                 for (int bj = 0; bj < 2; ++bj) { const size_t row = (size_t)(row0 + ai * HALF + m * 16); const int col = col0 + bj * HALF;
;                     float gf[8], nf[8], v[8]; unpack8(gw[m][bj], gf); unpack8(gn[m][bj], nf);
; #pragma unroll
;                     for (int j = 0; j < 4; ++j) { v[j] = gf[j] * acc[ai][bj][m][0][j]; v[4 + j] = gf[4 + j] * acc[ai][bj][m][1][j]; }
;                     if (last) { *(u32x4*)(MG + row * 1024 + col) = pack8(v); acc[ai][bj][m][0] = (f32x4){0.f, 0.f, 0.f, 0.f}; acc[ai][bj][m][1] = (f32x4){0.f, 0.f, 0.f, 0.f}; }
;                     else {
; #pragma unroll
;                         for (int j = 0; j < 4; ++j) { acc[ai][bj][m][0][j] = v[j] * __builtin_amdgcn_rcpf(fmaxf(nf[j], 1e-30f)); acc[ai][bj][m][1][j] = v[4 + j] * __builtin_amdgcn_rcpf(fmaxf(nf[4 + j], 1e-30f)); } }
.LBB0_297:
	v_lshlrev_b32_e32 v162, 16, v158
	v_and_b32_e32 v163, 0xffff0000, v158
	v_pk_mul_f32 v[164:165], v[110:111], v[162:163]
	v_lshlrev_b32_e32 v110, 16, v160
	v_and_b32_e32 v111, 0xffff0000, v160
	v_pk_mul_f32 v[162:163], v[106:107], v[110:111]
	v_lshlrev_b32_e32 v106, 16, v159
	v_and_b32_e32 v107, 0xffff0000, v159
	v_pk_mul_f32 v[158:159], v[112:113], v[106:107]
	v_lshlrev_b32_e32 v106, 16, v161
	v_and_b32_e32 v107, 0xffff0000, v161
	v_pk_mul_f32 v[160:161], v[108:109], v[106:107]
	s_and_b64 vcc, exec, s[38:39]
	s_mov_b64 s[30:31], -1
	s_cbranch_vccnz .LBB0_299
	v_lshlrev_b32_e32 v110, 16, v155
	v_lshlrev_b32_e32 v113, 16, v157
	v_max_f32_e32 v110, 0xda24260, v110
	v_rcp_f32_e32 v112, v110
	v_and_b32_e32 v111, 0xffff0000, v155
	v_max_f32_e32 v110, 0xda24260, v113
	v_lshlrev_b32_e32 v106, 16, v154
	v_and_b32_e32 v107, 0xffff0000, v154
	v_rcp_f32_e32 v154, v110
	v_lshlrev_b32_e32 v108, 16, v156
	v_and_b32_e32 v109, 0xffff0000, v156
	v_and_b32_e32 v155, 0xffff0000, v157
	v_max_f32_e32 v110, 0xda24260, v111
	v_rcp_f32_e32 v113, v110
	v_max_f32_e32 v106, 0xda24260, v106
	v_max_f32_e32 v108, 0xda24260, v108
	v_max_f32_e32 v107, 0xda24260, v107
	v_max_f32_e32 v109, 0xda24260, v109
	v_max_f32_e32 v110, 0xda24260, v155
	v_rcp_f32_e32 v106, v106
	v_rcp_f32_e32 v108, v108
	v_rcp_f32_e32 v107, v107
	v_rcp_f32_e32 v109, v109
	v_rcp_f32_e32 v155, v110
	v_pk_mul_f32 v[112:113], v[158:159], v[112:113]
	v_pk_mul_f32 v[110:111], v[164:165], v[106:107]
	v_pk_mul_f32 v[106:107], v[162:163], v[108:109]
	v_pk_mul_f32 v[108:109], v[160:161], v[154:155]
	s_mov_b64 s[30:31], 0

; __device__ __forceinline__ void unpack8(const u32x4 w, float (&f)[8]) { f[0] = bflo(w.x); f[1] = bfhi(w.x); f[2] = bflo(w.y); f[3] = bfhi(w.y); f[4] = bflo(w.z); f[5] = bfhi(w.z); f[6] = bflo(w.w); f[7] = bfhi(w.w); }
; __device__ __forceinline__ u32x4 pack8(const float (&f)[8]) { u32x4 w; w.x = cvt_pk_bf16(f[0], f[1]); w.y = cvt_pk_bf16(f[2], f[3]); w.z = cvt_pk_bf16(f[4], f[5]); w.w = cvt_pk_bf16(f[6], f[7]); return w; }
;     __device__ __forceinline__ void operator()(f32x4 (&acc)[2][2][4][2], const Unit& u, int wr, int wc, int fr, int fq) const {
;     ...
;             for (int m = 0; m < 4; ++m)
; #pragma unroll
;                 for (int bj = 0; bj < 2; ++bj) { const size_t row = (size_t)(row0 + ai * HALF + m * 16); const int col = col0 + bj * HALF;
;                     float gf[8], nf[8], v[8]; unpack8(gw[m][bj], gf); unpack8(gn[m][bj], nf);
; #pragma unroll
;                     for (int j = 0; j < 4; ++j) { v[j] = gf[j] * acc[ai][bj][m][0][j]; v[4 + j] = gf[4 + j] * acc[ai][bj][m][1][j]; }
;                     if (last) { *(u32x4*)(MG + row * 1024 + col) = pack8(v); acc[ai][bj][m][0] = (f32x4){0.f, 0.f, 0.f, 0.f}; acc[ai][bj][m][1] = (f32x4){0.f, 0.f, 0.f, 0.f}; }
;                     else {
; #pragma unroll
;                         for (int j = 0; j < 4; ++j) { acc[ai][bj][m][0][j] = v[j] * __builtin_amdgcn_rcpf(fmaxf(nf[j], 1e-30f)); acc[ai][bj][m][1][j] = v[4 + j] * __builtin_amdgcn_rcpf(fmaxf(nf[4 + j], 1e-30f)); } }
.LBB0_301:
	v_lshlrev_b32_e32 v156, 16, v150
	v_and_b32_e32 v157, 0xffff0000, v150
	v_pk_mul_f32 v[158:159], v[78:79], v[156:157]
	v_lshlrev_b32_e32 v78, 16, v152
	v_and_b32_e32 v79, 0xffff0000, v152
	v_pk_mul_f32 v[156:157], v[74:75], v[78:79]
	v_lshlrev_b32_e32 v74, 16, v151
	v_and_b32_e32 v75, 0xffff0000, v151
	v_pk_mul_f32 v[150:151], v[80:81], v[74:75]
	v_lshlrev_b32_e32 v74, 16, v153
	v_and_b32_e32 v75, 0xffff0000, v153
	v_pk_mul_f32 v[152:153], v[76:77], v[74:75]
	s_and_b64 vcc, exec, s[38:39]
	s_mov_b64 s[30:31], -1
	s_cbranch_vccnz .LBB0_303
	v_lshlrev_b32_e32 v78, 16, v147
	v_lshlrev_b32_e32 v81, 16, v149
	v_max_f32_e32 v78, 0xda24260, v78
	v_rcp_f32_e32 v80, v78
	v_and_b32_e32 v79, 0xffff0000, v147
	v_max_f32_e32 v78, 0xda24260, v81
	v_lshlrev_b32_e32 v74, 16, v146
	v_and_b32_e32 v75, 0xffff0000, v146
	v_rcp_f32_e32 v146, v78
	v_lshlrev_b32_e32 v76, 16, v148
	v_and_b32_e32 v77, 0xffff0000, v148
	v_and_b32_e32 v147, 0xffff0000, v149
	v_max_f32_e32 v78, 0xda24260, v79
	v_rcp_f32_e32 v81, v78
	v_max_f32_e32 v74, 0xda24260, v74
	v_max_f32_e32 v76, 0xda24260, v76
	v_max_f32_e32 v75, 0xda24260, v75
	v_max_f32_e32 v77, 0xda24260, v77
	v_max_f32_e32 v78, 0xda24260, v147
	v_rcp_f32_e32 v74, v74
	v_rcp_f32_e32 v76, v76
	v_rcp_f32_e32 v75, v75
	v_rcp_f32_e32 v77, v77
	v_rcp_f32_e32 v147, v78
	v_pk_mul_f32 v[80:81], v[150:151], v[80:81]
	v_pk_mul_f32 v[78:79], v[158:159], v[74:75]
	v_pk_mul_f32 v[74:75], v[156:157], v[76:77]
	v_pk_mul_f32 v[76:77], v[152:153], v[146:147]
	s_mov_b64 s[30:31], 0

; __device__ __forceinline__ void unpack8(const u32x4 w, float (&f)[8]) { f[0] = bflo(w.x); f[1] = bfhi(w.x); f[2] = bflo(w.y); f[3] = bfhi(w.y); f[4] = bflo(w.z); f[5] = bfhi(w.z); f[6] = bflo(w.w); f[7] = bfhi(w.w); }
; __device__ __forceinline__ u32x4 pack8(const float (&f)[8]) { u32x4 w; w.x = cvt_pk_bf16(f[0], f[1]); w.y = cvt_pk_bf16(f[2], f[3]); w.z = cvt_pk_bf16(f[4], f[5]); w.w = cvt_pk_bf16(f[6], f[7]); return w; }
;     __device__ __forceinline__ void operator()(f32x4 (&acc)[2][2][4][2], const Unit& u, int wr, int wc, int fr, int fq) const {
;     ...
;             for (int m = 0; m < 4; ++m)
; #pragma unroll
;                 for (int bj = 0; bj < 2; ++bj) { const size_t row = (size_t)(row0 + ai * HALF + m * 16); const int col = col0 + bj * HALF;
;                     float gf[8], nf[8], v[8]; unpack8(gw[m][bj], gf); unpack8(gn[m][bj], nf);
; #pragma unroll
;                     for (int j = 0; j < 4; ++j) { v[j] = gf[j] * acc[ai][bj][m][0][j]; v[4 + j] = gf[4 + j] * acc[ai][bj][m][1][j]; }
;                     if (last) { *(u32x4*)(MG + row * 1024 + col) = pack8(v); acc[ai][bj][m][0] = (f32x4){0.f, 0.f, 0.f, 0.f}; acc[ai][bj][m][1] = (f32x4){0.f, 0.f, 0.f, 0.f}; }
;                     else {
; #pragma unroll
;                         for (int j = 0; j < 4; ++j) { acc[ai][bj][m][0][j] = v[j] * __builtin_amdgcn_rcpf(fmaxf(nf[j], 1e-30f)); acc[ai][bj][m][1][j] = v[4 + j] * __builtin_amdgcn_rcpf(fmaxf(nf[4 + j], 1e-30f)); } }
.LBB0_305:
	v_lshlrev_b32_e32 v146, 16, v142
	v_and_b32_e32 v147, 0xffff0000, v142
	v_pk_mul_f32 v[148:149], v[102:103], v[146:147]
	v_lshlrev_b32_e32 v102, 16, v144
	v_and_b32_e32 v103, 0xffff0000, v144
	v_pk_mul_f32 v[146:147], v[98:99], v[102:103]
	v_lshlrev_b32_e32 v98, 16, v143
	v_and_b32_e32 v99, 0xffff0000, v143
	v_pk_mul_f32 v[142:143], v[104:105], v[98:99]
	v_lshlrev_b32_e32 v98, 16, v145
	v_and_b32_e32 v99, 0xffff0000, v145
	v_pk_mul_f32 v[144:145], v[100:101], v[98:99]
	s_and_b64 vcc, exec, s[38:39]
	s_mov_b64 s[30:31], -1
	s_cbranch_vccnz .LBB0_307
	v_lshlrev_b32_e32 v102, 16, v139
	v_lshlrev_b32_e32 v105, 16, v141
	v_max_f32_e32 v102, 0xda24260, v102
	v_rcp_f32_e32 v104, v102
	v_and_b32_e32 v103, 0xffff0000, v139
	v_max_f32_e32 v102, 0xda24260, v105
	v_lshlrev_b32_e32 v98, 16, v138
	v_and_b32_e32 v99, 0xffff0000, v138
	v_rcp_f32_e32 v138, v102
	v_lshlrev_b32_e32 v100, 16, v140
	v_and_b32_e32 v101, 0xffff0000, v140
	v_and_b32_e32 v139, 0xffff0000, v141
	v_max_f32_e32 v102, 0xda24260, v103
	v_rcp_f32_e32 v105, v102
	v_max_f32_e32 v98, 0xda24260, v98
	v_max_f32_e32 v100, 0xda24260, v100
	v_max_f32_e32 v99, 0xda24260, v99
	v_max_f32_e32 v101, 0xda24260, v101
	v_max_f32_e32 v102, 0xda24260, v139
	v_rcp_f32_e32 v98, v98
	v_rcp_f32_e32 v100, v100
	v_rcp_f32_e32 v99, v99
	v_rcp_f32_e32 v101, v101
	v_rcp_f32_e32 v139, v102
	v_pk_mul_f32 v[104:105], v[142:143], v[104:105]
	v_pk_mul_f32 v[102:103], v[148:149], v[98:99]
	v_pk_mul_f32 v[98:99], v[146:147], v[100:101]
	v_pk_mul_f32 v[100:101], v[144:145], v[138:139]
	s_mov_b64 s[30:31], 0

; __device__ __forceinline__ void unpack8(const u32x4 w, float (&f)[8]) { f[0] = bflo(w.x); f[1] = bfhi(w.x); f[2] = bflo(w.y); f[3] = bfhi(w.y); f[4] = bflo(w.z); f[5] = bfhi(w.z); f[6] = bflo(w.w); f[7] = bfhi(w.w); }
; __device__ __forceinline__ u32x4 pack8(const float (&f)[8]) { u32x4 w; w.x = cvt_pk_bf16(f[0], f[1]); w.y = cvt_pk_bf16(f[2], f[3]); w.z = cvt_pk_bf16(f[4], f[5]); w.w = cvt_pk_bf16(f[6], f[7]); return w; }
;     __device__ __forceinline__ void operator()(f32x4 (&acc)[2][2][4][2], const Unit& u, int wr, int wc, int fr, int fq) const {
;     ...
;             for (int m = 0; m < 4; ++m)
; #pragma unroll
;                 for (int bj = 0; bj < 2; ++bj) { const size_t row = (size_t)(row0 + ai * HALF + m * 16); const int col = col0 + bj * HALF;
;                     float gf[8], nf[8], v[8]; unpack8(gw[m][bj], gf); unpack8(gn[m][bj], nf);
; #pragma unroll
;                     for (int j = 0; j < 4; ++j) { v[j] = gf[j] * acc[ai][bj][m][0][j]; v[4 + j] = gf[4 + j] * acc[ai][bj][m][1][j]; }
;                     if (last) { *(u32x4*)(MG + row * 1024 + col) = pack8(v); acc[ai][bj][m][0] = (f32x4){0.f, 0.f, 0.f, 0.f}; acc[ai][bj][m][1] = (f32x4){0.f, 0.f, 0.f, 0.f}; }
;                     else {
; #pragma unroll
;                         for (int j = 0; j < 4; ++j) { acc[ai][bj][m][0][j] = v[j] * __builtin_amdgcn_rcpf(fmaxf(nf[j], 1e-30f)); acc[ai][bj][m][1][j] = v[4 + j] * __builtin_amdgcn_rcpf(fmaxf(nf[4 + j], 1e-30f)); } }
.LBB0_309:
	v_lshlrev_b32_e32 v140, 16, v134
	v_and_b32_e32 v141, 0xffff0000, v134
	v_pk_mul_f32 v[142:143], v[70:71], v[140:141]
	v_lshlrev_b32_e32 v70, 16, v136
	v_and_b32_e32 v71, 0xffff0000, v136
	v_pk_mul_f32 v[140:141], v[66:67], v[70:71]
	v_lshlrev_b32_e32 v66, 16, v135
	v_and_b32_e32 v67, 0xffff0000, v135
	v_pk_mul_f32 v[134:135], v[72:73], v[66:67]
	v_lshlrev_b32_e32 v66, 16, v137
	v_and_b32_e32 v67, 0xffff0000, v137
	v_pk_mul_f32 v[136:137], v[68:69], v[66:67]
	s_and_b64 vcc, exec, s[38:39]
	s_mov_b64 s[30:31], -1
	s_cbranch_vccnz .LBB0_311
	v_lshlrev_b32_e32 v70, 16, v131
	v_lshlrev_b32_e32 v73, 16, v133
	v_max_f32_e32 v70, 0xda24260, v70
	v_rcp_f32_e32 v72, v70
	v_and_b32_e32 v71, 0xffff0000, v131
	v_max_f32_e32 v70, 0xda24260, v73
	v_lshlrev_b32_e32 v66, 16, v130
	v_and_b32_e32 v67, 0xffff0000, v130
	v_rcp_f32_e32 v130, v70
	v_lshlrev_b32_e32 v68, 16, v132
	v_and_b32_e32 v69, 0xffff0000, v132
	v_and_b32_e32 v131, 0xffff0000, v133
	v_max_f32_e32 v70, 0xda24260, v71
	v_rcp_f32_e32 v73, v70
	v_max_f32_e32 v66, 0xda24260, v66
	v_max_f32_e32 v68, 0xda24260, v68
	v_max_f32_e32 v67, 0xda24260, v67
	v_max_f32_e32 v69, 0xda24260, v69
	v_max_f32_e32 v70, 0xda24260, v131
	v_rcp_f32_e32 v66, v66
	v_rcp_f32_e32 v68, v68
	v_rcp_f32_e32 v67, v67
	v_rcp_f32_e32 v69, v69
	v_rcp_f32_e32 v131, v70
	v_pk_mul_f32 v[72:73], v[134:135], v[72:73]
	v_pk_mul_f32 v[70:71], v[142:143], v[66:67]
	v_pk_mul_f32 v[66:67], v[140:141], v[68:69]
	v_pk_mul_f32 v[68:69], v[136:137], v[130:131]
	s_mov_b64 s[30:31], 0

; __device__ __forceinline__ void unpack8(const u32x4 w, float (&f)[8]) { f[0] = bflo(w.x); f[1] = bfhi(w.x); f[2] = bflo(w.y); f[3] = bfhi(w.y); f[4] = bflo(w.z); f[5] = bfhi(w.z); f[6] = bflo(w.w); f[7] = bfhi(w.w); }
; __device__ __forceinline__ u32x4 pack8(const float (&f)[8]) { u32x4 w; w.x = cvt_pk_bf16(f[0], f[1]); w.y = cvt_pk_bf16(f[2], f[3]); w.z = cvt_pk_bf16(f[4], f[5]); w.w = cvt_pk_bf16(f[6], f[7]); return w; }
;     __device__ __forceinline__ void operator()(f32x4 (&acc)[2][2][4][2], const Unit& u, int wr, int wc, int fr, int fq) const {
;     ...
;             for (int m = 0; m < 4; ++m)
; #pragma unroll
;                 for (int bj = 0; bj < 2; ++bj) { const size_t row = (size_t)(row0 + ai * HALF + m * 16); const int col = col0 + bj * HALF;
;                     float gf[8], nf[8], v[8]; unpack8(gw[m][bj], gf); unpack8(gn[m][bj], nf);
; #pragma unroll
;                     for (int j = 0; j < 4; ++j) { v[j] = gf[j] * acc[ai][bj][m][0][j]; v[4 + j] = gf[4 + j] * acc[ai][bj][m][1][j]; }
;                     if (last) { *(u32x4*)(MG + row * 1024 + col) = pack8(v); acc[ai][bj][m][0] = (f32x4){0.f, 0.f, 0.f, 0.f}; acc[ai][bj][m][1] = (f32x4){0.f, 0.f, 0.f, 0.f}; }
;                     else {
; #pragma unroll
;                         for (int j = 0; j < 4; ++j) { acc[ai][bj][m][0][j] = v[j] * __builtin_amdgcn_rcpf(fmaxf(nf[j], 1e-30f)); acc[ai][bj][m][1][j] = v[4 + j] * __builtin_amdgcn_rcpf(fmaxf(nf[4 + j], 1e-30f)); } }
.LBB0_329:
	s_waitcnt vmcnt(7)
	v_lshlrev_b32_e32 v224, 16, v190
	v_and_b32_e32 v225, 0xffff0000, v190
	v_pk_mul_f32 v[226:227], v[62:63], v[224:225]
	v_lshlrev_b32_e32 v62, 16, v192
	v_and_b32_e32 v63, 0xffff0000, v192
	v_pk_mul_f32 v[224:225], v[58:59], v[62:63]
	v_lshlrev_b32_e32 v58, 16, v191
	v_and_b32_e32 v59, 0xffff0000, v191
	v_pk_mul_f32 v[190:191], v[64:65], v[58:59]
	v_lshlrev_b32_e32 v58, 16, v193
	v_and_b32_e32 v59, 0xffff0000, v193
	v_pk_mul_f32 v[192:193], v[60:61], v[58:59]
	s_and_b64 vcc, exec, s[38:39]
	s_mov_b64 s[0:1], -1
	s_cbranch_vccnz .LBB0_331
	v_lshlrev_b32_e32 v62, 16, v187
	v_lshlrev_b32_e32 v65, 16, v189
	v_max_f32_e32 v62, 0xda24260, v62
	v_rcp_f32_e32 v64, v62
	v_and_b32_e32 v63, 0xffff0000, v187
	v_max_f32_e32 v62, 0xda24260, v65
	v_lshlrev_b32_e32 v58, 16, v186
	v_and_b32_e32 v59, 0xffff0000, v186
	v_rcp_f32_e32 v186, v62
	v_lshlrev_b32_e32 v60, 16, v188
	v_and_b32_e32 v61, 0xffff0000, v188
	v_and_b32_e32 v187, 0xffff0000, v189
	v_max_f32_e32 v62, 0xda24260, v63
	v_rcp_f32_e32 v65, v62
	v_max_f32_e32 v58, 0xda24260, v58
	v_max_f32_e32 v60, 0xda24260, v60
	v_max_f32_e32 v59, 0xda24260, v59
	v_max_f32_e32 v61, 0xda24260, v61
	v_max_f32_e32 v62, 0xda24260, v187
	v_rcp_f32_e32 v58, v58
	v_rcp_f32_e32 v60, v60
	v_rcp_f32_e32 v59, v59
	v_rcp_f32_e32 v61, v61
	v_rcp_f32_e32 v187, v62
	v_pk_mul_f32 v[64:65], v[190:191], v[64:65]
	v_pk_mul_f32 v[62:63], v[226:227], v[58:59]
	v_pk_mul_f32 v[58:59], v[224:225], v[60:61]
	v_pk_mul_f32 v[60:61], v[192:193], v[186:187]
	s_mov_b64 s[0:1], 0

; __device__ __forceinline__ void unpack8(const u32x4 w, float (&f)[8]) { f[0] = bflo(w.x); f[1] = bfhi(w.x); f[2] = bflo(w.y); f[3] = bfhi(w.y); f[4] = bflo(w.z); f[5] = bfhi(w.z); f[6] = bflo(w.w); f[7] = bfhi(w.w); }
; __device__ __forceinline__ u32x4 pack8(const float (&f)[8]) { u32x4 w; w.x = cvt_pk_bf16(f[0], f[1]); w.y = cvt_pk_bf16(f[2], f[3]); w.z = cvt_pk_bf16(f[4], f[5]); w.w = cvt_pk_bf16(f[6], f[7]); return w; }
;     __device__ __forceinline__ void operator()(f32x4 (&acc)[2][2][4][2], const Unit& u, int wr, int wc, int fr, int fq) const {
;     ...
;             for (int m = 0; m < 4; ++m)
; #pragma unroll
;                 for (int bj = 0; bj < 2; ++bj) { const size_t row = (size_t)(row0 + ai * HALF + m * 16); const int col = col0 + bj * HALF;
;                     float gf[8], nf[8], v[8]; unpack8(gw[m][bj], gf); unpack8(gn[m][bj], nf);
; #pragma unroll
;                     for (int j = 0; j < 4; ++j) { v[j] = gf[j] * acc[ai][bj][m][0][j]; v[4 + j] = gf[4 + j] * acc[ai][bj][m][1][j]; }
;                     if (last) { *(u32x4*)(MG + row * 1024 + col) = pack8(v); acc[ai][bj][m][0] = (f32x4){0.f, 0.f, 0.f, 0.f}; acc[ai][bj][m][1] = (f32x4){0.f, 0.f, 0.f, 0.f}; }
;                     else {
; #pragma unroll
;                         for (int j = 0; j < 4; ++j) { acc[ai][bj][m][0][j] = v[j] * __builtin_amdgcn_rcpf(fmaxf(nf[j], 1e-30f)); acc[ai][bj][m][1][j] = v[4 + j] * __builtin_amdgcn_rcpf(fmaxf(nf[4 + j], 1e-30f)); } }
.LBB0_333:
	s_waitcnt vmcnt(6)
	v_lshlrev_b32_e32 v188, 16, v182
	v_and_b32_e32 v189, 0xffff0000, v182
	v_pk_mul_f32 v[190:191], v[30:31], v[188:189]
	v_lshlrev_b32_e32 v30, 16, v184
	v_and_b32_e32 v31, 0xffff0000, v184
	v_pk_mul_f32 v[188:189], v[26:27], v[30:31]
	v_lshlrev_b32_e32 v26, 16, v183
	v_and_b32_e32 v27, 0xffff0000, v183
	v_pk_mul_f32 v[182:183], v[32:33], v[26:27]
	v_lshlrev_b32_e32 v26, 16, v185
	v_and_b32_e32 v27, 0xffff0000, v185
	v_pk_mul_f32 v[184:185], v[28:29], v[26:27]
	s_and_b64 vcc, exec, s[38:39]
	s_mov_b64 s[0:1], -1
	s_cbranch_vccnz .LBB0_335
	v_lshlrev_b32_e32 v30, 16, v179
	v_lshlrev_b32_e32 v33, 16, v181
	v_max_f32_e32 v30, 0xda24260, v30
	v_rcp_f32_e32 v32, v30
	v_and_b32_e32 v31, 0xffff0000, v179
	v_max_f32_e32 v30, 0xda24260, v33
	v_lshlrev_b32_e32 v26, 16, v178
	v_and_b32_e32 v27, 0xffff0000, v178
	v_rcp_f32_e32 v178, v30
	v_lshlrev_b32_e32 v28, 16, v180
	v_and_b32_e32 v29, 0xffff0000, v180
	v_and_b32_e32 v179, 0xffff0000, v181
	v_max_f32_e32 v30, 0xda24260, v31
	v_rcp_f32_e32 v33, v30
	v_max_f32_e32 v26, 0xda24260, v26
	v_max_f32_e32 v28, 0xda24260, v28
	v_max_f32_e32 v27, 0xda24260, v27
	v_max_f32_e32 v29, 0xda24260, v29
	v_max_f32_e32 v30, 0xda24260, v179
	v_rcp_f32_e32 v26, v26
	v_rcp_f32_e32 v28, v28
	v_rcp_f32_e32 v27, v27
	v_rcp_f32_e32 v29, v29
	v_rcp_f32_e32 v179, v30
	v_pk_mul_f32 v[32:33], v[182:183], v[32:33]
	v_pk_mul_f32 v[30:31], v[190:191], v[26:27]
	v_pk_mul_f32 v[26:27], v[188:189], v[28:29]
	v_pk_mul_f32 v[28:29], v[184:185], v[178:179]
	s_mov_b64 s[0:1], 0

; __device__ __forceinline__ void unpack8(const u32x4 w, float (&f)[8]) { f[0] = bflo(w.x); f[1] = bfhi(w.x); f[2] = bflo(w.y); f[3] = bfhi(w.y); f[4] = bflo(w.z); f[5] = bfhi(w.z); f[6] = bflo(w.w); f[7] = bfhi(w.w); }
; __device__ __forceinline__ u32x4 pack8(const float (&f)[8]) { u32x4 w; w.x = cvt_pk_bf16(f[0], f[1]); w.y = cvt_pk_bf16(f[2], f[3]); w.z = cvt_pk_bf16(f[4], f[5]); w.w = cvt_pk_bf16(f[6], f[7]); return w; }
;     __device__ __forceinline__ void operator()(f32x4 (&acc)[2][2][4][2], const Unit& u, int wr, int wc, int fr, int fq) const {
;     ...
;             for (int m = 0; m < 4; ++m)
; #pragma unroll
;                 for (int bj = 0; bj < 2; ++bj) { const size_t row = (size_t)(row0 + ai * HALF + m * 16); const int col = col0 + bj * HALF;
;                     float gf[8], nf[8], v[8]; unpack8(gw[m][bj], gf); unpack8(gn[m][bj], nf);
; #pragma unroll
;                     for (int j = 0; j < 4; ++j) { v[j] = gf[j] * acc[ai][bj][m][0][j]; v[4 + j] = gf[4 + j] * acc[ai][bj][m][1][j]; }
;                     if (last) { *(u32x4*)(MG + row * 1024 + col) = pack8(v); acc[ai][bj][m][0] = (f32x4){0.f, 0.f, 0.f, 0.f}; acc[ai][bj][m][1] = (f32x4){0.f, 0.f, 0.f, 0.f}; }
;                     else {
; #pragma unroll
;                         for (int j = 0; j < 4; ++j) { acc[ai][bj][m][0][j] = v[j] * __builtin_amdgcn_rcpf(fmaxf(nf[j], 1e-30f)); acc[ai][bj][m][1][j] = v[4 + j] * __builtin_amdgcn_rcpf(fmaxf(nf[4 + j], 1e-30f)); } }
.LBB0_337:
	s_waitcnt vmcnt(5)
	v_lshlrev_b32_e32 v178, 16, v174
	v_and_b32_e32 v179, 0xffff0000, v174
	v_pk_mul_f32 v[180:181], v[54:55], v[178:179]
	v_lshlrev_b32_e32 v54, 16, v176
	v_and_b32_e32 v55, 0xffff0000, v176
	v_pk_mul_f32 v[178:179], v[50:51], v[54:55]
	v_lshlrev_b32_e32 v50, 16, v175
	v_and_b32_e32 v51, 0xffff0000, v175
	v_pk_mul_f32 v[174:175], v[56:57], v[50:51]
	v_lshlrev_b32_e32 v50, 16, v177
	v_and_b32_e32 v51, 0xffff0000, v177
	v_pk_mul_f32 v[176:177], v[52:53], v[50:51]
	s_and_b64 vcc, exec, s[38:39]
	s_mov_b64 s[0:1], -1
	s_cbranch_vccnz .LBB0_339
	v_lshlrev_b32_e32 v54, 16, v171
	v_lshlrev_b32_e32 v57, 16, v173
	v_max_f32_e32 v54, 0xda24260, v54
	v_rcp_f32_e32 v56, v54
	v_and_b32_e32 v55, 0xffff0000, v171
	v_max_f32_e32 v54, 0xda24260, v57
	v_lshlrev_b32_e32 v50, 16, v170
	v_and_b32_e32 v51, 0xffff0000, v170
	v_rcp_f32_e32 v170, v54
	v_lshlrev_b32_e32 v52, 16, v172
	v_and_b32_e32 v53, 0xffff0000, v172
	v_and_b32_e32 v171, 0xffff0000, v173
	v_max_f32_e32 v54, 0xda24260, v55
	v_rcp_f32_e32 v57, v54
	v_max_f32_e32 v50, 0xda24260, v50
	v_max_f32_e32 v52, 0xda24260, v52
	v_max_f32_e32 v51, 0xda24260, v51
	v_max_f32_e32 v53, 0xda24260, v53
	v_max_f32_e32 v54, 0xda24260, v171
	v_rcp_f32_e32 v50, v50
	v_rcp_f32_e32 v52, v52
	v_rcp_f32_e32 v51, v51
	v_rcp_f32_e32 v53, v53
	v_rcp_f32_e32 v171, v54
	v_pk_mul_f32 v[56:57], v[174:175], v[56:57]
	v_pk_mul_f32 v[54:55], v[180:181], v[50:51]
	v_pk_mul_f32 v[50:51], v[178:179], v[52:53]
	v_pk_mul_f32 v[52:53], v[176:177], v[170:171]
	s_mov_b64 s[0:1], 0

; __device__ __forceinline__ void unpack8(const u32x4 w, float (&f)[8]) { f[0] = bflo(w.x); f[1] = bfhi(w.x); f[2] = bflo(w.y); f[3] = bfhi(w.y); f[4] = bflo(w.z); f[5] = bfhi(w.z); f[6] = bflo(w.w); f[7] = bfhi(w.w); }
; __device__ __forceinline__ u32x4 pack8(const float (&f)[8]) { u32x4 w; w.x = cvt_pk_bf16(f[0], f[1]); w.y = cvt_pk_bf16(f[2], f[3]); w.z = cvt_pk_bf16(f[4], f[5]); w.w = cvt_pk_bf16(f[6], f[7]); return w; }
;     __device__ __forceinline__ void operator()(f32x4 (&acc)[2][2][4][2], const Unit& u, int wr, int wc, int fr, int fq) const {
;     ...
;             for (int m = 0; m < 4; ++m)
; #pragma unroll
;                 for (int bj = 0; bj < 2; ++bj) { const size_t row = (size_t)(row0 + ai * HALF + m * 16); const int col = col0 + bj * HALF;
;                     float gf[8], nf[8], v[8]; unpack8(gw[m][bj], gf); unpack8(gn[m][bj], nf);
; #pragma unroll
;                     for (int j = 0; j < 4; ++j) { v[j] = gf[j] * acc[ai][bj][m][0][j]; v[4 + j] = gf[4 + j] * acc[ai][bj][m][1][j]; }
;                     if (last) { *(u32x4*)(MG + row * 1024 + col) = pack8(v); acc[ai][bj][m][0] = (f32x4){0.f, 0.f, 0.f, 0.f}; acc[ai][bj][m][1] = (f32x4){0.f, 0.f, 0.f, 0.f}; }
;                     else {
; #pragma unroll
;                         for (int j = 0; j < 4; ++j) { acc[ai][bj][m][0][j] = v[j] * __builtin_amdgcn_rcpf(fmaxf(nf[j], 1e-30f)); acc[ai][bj][m][1][j] = v[4 + j] * __builtin_amdgcn_rcpf(fmaxf(nf[4 + j], 1e-30f)); } }
.LBB0_341:
	s_waitcnt vmcnt(4)
	v_lshlrev_b32_e32 v172, 16, v166
	v_and_b32_e32 v173, 0xffff0000, v166
	v_pk_mul_f32 v[174:175], v[22:23], v[172:173]
	v_lshlrev_b32_e32 v22, 16, v168
	v_and_b32_e32 v23, 0xffff0000, v168
	v_pk_mul_f32 v[172:173], v[18:19], v[22:23]
	v_lshlrev_b32_e32 v18, 16, v167
	v_and_b32_e32 v19, 0xffff0000, v167
	v_pk_mul_f32 v[166:167], v[24:25], v[18:19]
	v_lshlrev_b32_e32 v18, 16, v169
	v_and_b32_e32 v19, 0xffff0000, v169
	v_pk_mul_f32 v[168:169], v[20:21], v[18:19]
	s_and_b64 vcc, exec, s[38:39]
	s_mov_b64 s[0:1], -1
	s_cbranch_vccnz .LBB0_343
	v_lshlrev_b32_e32 v22, 16, v163
	v_lshlrev_b32_e32 v25, 16, v165
	v_max_f32_e32 v22, 0xda24260, v22
	v_rcp_f32_e32 v24, v22
	v_and_b32_e32 v23, 0xffff0000, v163
	v_max_f32_e32 v22, 0xda24260, v25
	v_lshlrev_b32_e32 v18, 16, v162
	v_and_b32_e32 v19, 0xffff0000, v162
	v_rcp_f32_e32 v162, v22
	v_lshlrev_b32_e32 v20, 16, v164
	v_and_b32_e32 v21, 0xffff0000, v164
	v_and_b32_e32 v163, 0xffff0000, v165
	v_max_f32_e32 v22, 0xda24260, v23
	v_rcp_f32_e32 v25, v22
	v_max_f32_e32 v18, 0xda24260, v18
	v_max_f32_e32 v20, 0xda24260, v20
	v_max_f32_e32 v19, 0xda24260, v19
	v_max_f32_e32 v21, 0xda24260, v21
	v_max_f32_e32 v22, 0xda24260, v163
	v_rcp_f32_e32 v18, v18
	v_rcp_f32_e32 v20, v20
	v_rcp_f32_e32 v19, v19
	v_rcp_f32_e32 v21, v21
	v_rcp_f32_e32 v163, v22
	v_pk_mul_f32 v[24:25], v[166:167], v[24:25]
	v_pk_mul_f32 v[22:23], v[174:175], v[18:19]
	v_pk_mul_f32 v[18:19], v[172:173], v[20:21]
	v_pk_mul_f32 v[20:21], v[168:169], v[162:163]
	s_mov_b64 s[0:1], 0

; __device__ __forceinline__ void unpack8(const u32x4 w, float (&f)[8]) { f[0] = bflo(w.x); f[1] = bfhi(w.x); f[2] = bflo(w.y); f[3] = bfhi(w.y); f[4] = bflo(w.z); f[5] = bfhi(w.z); f[6] = bflo(w.w); f[7] = bfhi(w.w); }
; __device__ __forceinline__ u32x4 pack8(const float (&f)[8]) { u32x4 w; w.x = cvt_pk_bf16(f[0], f[1]); w.y = cvt_pk_bf16(f[2], f[3]); w.z = cvt_pk_bf16(f[4], f[5]); w.w = cvt_pk_bf16(f[6], f[7]); return w; }
;     __device__ __forceinline__ void operator()(f32x4 (&acc)[2][2][4][2], const Unit& u, int wr, int wc, int fr, int fq) const {
;     ...
;             for (int m = 0; m < 4; ++m)
; #pragma unroll
;                 for (int bj = 0; bj < 2; ++bj) { const size_t row = (size_t)(row0 + ai * HALF + m * 16); const int col = col0 + bj * HALF;
;                     float gf[8], nf[8], v[8]; unpack8(gw[m][bj], gf); unpack8(gn[m][bj], nf);
; #pragma unroll
;                     for (int j = 0; j < 4; ++j) { v[j] = gf[j] * acc[ai][bj][m][0][j]; v[4 + j] = gf[4 + j] * acc[ai][bj][m][1][j]; }
;                     if (last) { *(u32x4*)(MG + row * 1024 + col) = pack8(v); acc[ai][bj][m][0] = (f32x4){0.f, 0.f, 0.f, 0.f}; acc[ai][bj][m][1] = (f32x4){0.f, 0.f, 0.f, 0.f}; }
;                     else {
; #pragma unroll
;                         for (int j = 0; j < 4; ++j) { acc[ai][bj][m][0][j] = v[j] * __builtin_amdgcn_rcpf(fmaxf(nf[j], 1e-30f)); acc[ai][bj][m][1][j] = v[4 + j] * __builtin_amdgcn_rcpf(fmaxf(nf[4 + j], 1e-30f)); } }
.LBB0_345:
	s_waitcnt vmcnt(3)
	v_lshlrev_b32_e32 v162, 16, v158
	v_and_b32_e32 v163, 0xffff0000, v158
	v_pk_mul_f32 v[164:165], v[46:47], v[162:163]
	v_lshlrev_b32_e32 v46, 16, v160
	v_and_b32_e32 v47, 0xffff0000, v160
	v_pk_mul_f32 v[162:163], v[42:43], v[46:47]
	v_lshlrev_b32_e32 v42, 16, v159
	v_and_b32_e32 v43, 0xffff0000, v159
	v_pk_mul_f32 v[158:159], v[48:49], v[42:43]
	v_lshlrev_b32_e32 v42, 16, v161
	v_and_b32_e32 v43, 0xffff0000, v161
	v_pk_mul_f32 v[160:161], v[44:45], v[42:43]
	s_and_b64 vcc, exec, s[38:39]
	s_mov_b64 s[0:1], -1
	s_cbranch_vccnz .LBB0_347
	v_lshlrev_b32_e32 v46, 16, v155
	v_lshlrev_b32_e32 v49, 16, v157
	v_max_f32_e32 v46, 0xda24260, v46
	v_rcp_f32_e32 v48, v46
	v_and_b32_e32 v47, 0xffff0000, v155
	v_max_f32_e32 v46, 0xda24260, v49
	v_lshlrev_b32_e32 v42, 16, v154
	v_and_b32_e32 v43, 0xffff0000, v154
	v_rcp_f32_e32 v154, v46
	v_lshlrev_b32_e32 v44, 16, v156
	v_and_b32_e32 v45, 0xffff0000, v156
	v_and_b32_e32 v155, 0xffff0000, v157
	v_max_f32_e32 v46, 0xda24260, v47
	v_rcp_f32_e32 v49, v46
	v_max_f32_e32 v42, 0xda24260, v42
	v_max_f32_e32 v44, 0xda24260, v44
	v_max_f32_e32 v43, 0xda24260, v43
	v_max_f32_e32 v45, 0xda24260, v45
	v_max_f32_e32 v46, 0xda24260, v155
	v_rcp_f32_e32 v42, v42
	v_rcp_f32_e32 v44, v44
	v_rcp_f32_e32 v43, v43
	v_rcp_f32_e32 v45, v45
	v_rcp_f32_e32 v155, v46
	v_pk_mul_f32 v[48:49], v[158:159], v[48:49]
	v_pk_mul_f32 v[46:47], v[164:165], v[42:43]
	v_pk_mul_f32 v[42:43], v[162:163], v[44:45]
	v_pk_mul_f32 v[44:45], v[160:161], v[154:155]
	s_mov_b64 s[0:1], 0

; __device__ __forceinline__ void unpack8(const u32x4 w, float (&f)[8]) { f[0] = bflo(w.x); f[1] = bfhi(w.x); f[2] = bflo(w.y); f[3] = bfhi(w.y); f[4] = bflo(w.z); f[5] = bfhi(w.z); f[6] = bflo(w.w); f[7] = bfhi(w.w); }
; __device__ __forceinline__ u32x4 pack8(const float (&f)[8]) { u32x4 w; w.x = cvt_pk_bf16(f[0], f[1]); w.y = cvt_pk_bf16(f[2], f[3]); w.z = cvt_pk_bf16(f[4], f[5]); w.w = cvt_pk_bf16(f[6], f[7]); return w; }
;     __device__ __forceinline__ void operator()(f32x4 (&acc)[2][2][4][2], const Unit& u, int wr, int wc, int fr, int fq) const {
;     ...
;             for (int m = 0; m < 4; ++m)
; #pragma unroll
;                 for (int bj = 0; bj < 2; ++bj) { const size_t row = (size_t)(row0 + ai * HALF + m * 16); const int col = col0 + bj * HALF;
;                     float gf[8], nf[8], v[8]; unpack8(gw[m][bj], gf); unpack8(gn[m][bj], nf);
; #pragma unroll
;                     for (int j = 0; j < 4; ++j) { v[j] = gf[j] * acc[ai][bj][m][0][j]; v[4 + j] = gf[4 + j] * acc[ai][bj][m][1][j]; }
;                     if (last) { *(u32x4*)(MG + row * 1024 + col) = pack8(v); acc[ai][bj][m][0] = (f32x4){0.f, 0.f, 0.f, 0.f}; acc[ai][bj][m][1] = (f32x4){0.f, 0.f, 0.f, 0.f}; }
;                     else {
; #pragma unroll
;                         for (int j = 0; j < 4; ++j) { acc[ai][bj][m][0][j] = v[j] * __builtin_amdgcn_rcpf(fmaxf(nf[j], 1e-30f)); acc[ai][bj][m][1][j] = v[4 + j] * __builtin_amdgcn_rcpf(fmaxf(nf[4 + j], 1e-30f)); } }
.LBB0_349:
	s_waitcnt vmcnt(2)
	v_lshlrev_b32_e32 v156, 16, v150
	v_and_b32_e32 v157, 0xffff0000, v150
	v_pk_mul_f32 v[158:159], v[14:15], v[156:157]
	v_lshlrev_b32_e32 v14, 16, v152
	v_and_b32_e32 v15, 0xffff0000, v152
	v_pk_mul_f32 v[156:157], v[10:11], v[14:15]
	v_lshlrev_b32_e32 v10, 16, v151
	v_and_b32_e32 v11, 0xffff0000, v151
	v_pk_mul_f32 v[150:151], v[16:17], v[10:11]
	v_lshlrev_b32_e32 v10, 16, v153
	v_and_b32_e32 v11, 0xffff0000, v153
	v_pk_mul_f32 v[152:153], v[12:13], v[10:11]
	s_and_b64 vcc, exec, s[38:39]
	s_mov_b64 s[0:1], -1
	s_cbranch_vccnz .LBB0_351
	v_lshlrev_b32_e32 v14, 16, v147
	v_lshlrev_b32_e32 v17, 16, v149
	v_max_f32_e32 v14, 0xda24260, v14
	v_rcp_f32_e32 v16, v14
	v_and_b32_e32 v15, 0xffff0000, v147
	v_max_f32_e32 v14, 0xda24260, v17
	v_lshlrev_b32_e32 v10, 16, v146
	v_and_b32_e32 v11, 0xffff0000, v146
	v_rcp_f32_e32 v146, v14
	v_lshlrev_b32_e32 v12, 16, v148
	v_and_b32_e32 v13, 0xffff0000, v148
	v_and_b32_e32 v147, 0xffff0000, v149
	v_max_f32_e32 v14, 0xda24260, v15
	v_rcp_f32_e32 v17, v14
	v_max_f32_e32 v10, 0xda24260, v10
	v_max_f32_e32 v12, 0xda24260, v12
	v_max_f32_e32 v11, 0xda24260, v11
	v_max_f32_e32 v13, 0xda24260, v13
	v_max_f32_e32 v14, 0xda24260, v147
	v_rcp_f32_e32 v10, v10
	v_rcp_f32_e32 v12, v12
	v_rcp_f32_e32 v11, v11
	v_rcp_f32_e32 v13, v13
	v_rcp_f32_e32 v147, v14
	v_pk_mul_f32 v[16:17], v[150:151], v[16:17]
	v_pk_mul_f32 v[14:15], v[158:159], v[10:11]
	v_pk_mul_f32 v[10:11], v[156:157], v[12:13]
	v_pk_mul_f32 v[12:13], v[152:153], v[146:147]
	s_mov_b64 s[0:1], 0

; __device__ __forceinline__ void unpack8(const u32x4 w, float (&f)[8]) { f[0] = bflo(w.x); f[1] = bfhi(w.x); f[2] = bflo(w.y); f[3] = bfhi(w.y); f[4] = bflo(w.z); f[5] = bfhi(w.z); f[6] = bflo(w.w); f[7] = bfhi(w.w); }
; __device__ __forceinline__ u32x4 pack8(const float (&f)[8]) { u32x4 w; w.x = cvt_pk_bf16(f[0], f[1]); w.y = cvt_pk_bf16(f[2], f[3]); w.z = cvt_pk_bf16(f[4], f[5]); w.w = cvt_pk_bf16(f[6], f[7]); return w; }
;     __device__ __forceinline__ void operator()(f32x4 (&acc)[2][2][4][2], const Unit& u, int wr, int wc, int fr, int fq) const {
;     ...
;             for (int m = 0; m < 4; ++m)
; #pragma unroll
;                 for (int bj = 0; bj < 2; ++bj) { const size_t row = (size_t)(row0 + ai * HALF + m * 16); const int col = col0 + bj * HALF;
;                     float gf[8], nf[8], v[8]; unpack8(gw[m][bj], gf); unpack8(gn[m][bj], nf);
; #pragma unroll
;                     for (int j = 0; j < 4; ++j) { v[j] = gf[j] * acc[ai][bj][m][0][j]; v[4 + j] = gf[4 + j] * acc[ai][bj][m][1][j]; }
;                     if (last) { *(u32x4*)(MG + row * 1024 + col) = pack8(v); acc[ai][bj][m][0] = (f32x4){0.f, 0.f, 0.f, 0.f}; acc[ai][bj][m][1] = (f32x4){0.f, 0.f, 0.f, 0.f}; }
;                     else {
; #pragma unroll
;                         for (int j = 0; j < 4; ++j) { acc[ai][bj][m][0][j] = v[j] * __builtin_amdgcn_rcpf(fmaxf(nf[j], 1e-30f)); acc[ai][bj][m][1][j] = v[4 + j] * __builtin_amdgcn_rcpf(fmaxf(nf[4 + j], 1e-30f)); } }
.LBB0_353:
	s_waitcnt vmcnt(1)
	v_lshlrev_b32_e32 v146, 16, v142
	v_and_b32_e32 v147, 0xffff0000, v142
	v_pk_mul_f32 v[148:149], v[38:39], v[146:147]
	v_lshlrev_b32_e32 v38, 16, v144
	v_and_b32_e32 v39, 0xffff0000, v144
	v_pk_mul_f32 v[146:147], v[34:35], v[38:39]
	v_lshlrev_b32_e32 v34, 16, v143
	v_and_b32_e32 v35, 0xffff0000, v143
	v_pk_mul_f32 v[142:143], v[40:41], v[34:35]
	v_lshlrev_b32_e32 v34, 16, v145
	v_and_b32_e32 v35, 0xffff0000, v145
	v_pk_mul_f32 v[144:145], v[36:37], v[34:35]
	s_and_b64 vcc, exec, s[38:39]
	s_mov_b64 s[0:1], -1
	s_cbranch_vccnz .LBB0_355
	v_lshlrev_b32_e32 v38, 16, v139
	v_lshlrev_b32_e32 v41, 16, v141
	v_max_f32_e32 v38, 0xda24260, v38
	v_rcp_f32_e32 v40, v38
	v_and_b32_e32 v39, 0xffff0000, v139
	v_max_f32_e32 v38, 0xda24260, v41
	v_lshlrev_b32_e32 v34, 16, v138
	v_and_b32_e32 v35, 0xffff0000, v138
	v_rcp_f32_e32 v138, v38
	v_lshlrev_b32_e32 v36, 16, v140
	v_and_b32_e32 v37, 0xffff0000, v140
	v_and_b32_e32 v139, 0xffff0000, v141
	v_max_f32_e32 v38, 0xda24260, v39
	v_rcp_f32_e32 v41, v38
	v_max_f32_e32 v34, 0xda24260, v34
	v_max_f32_e32 v36, 0xda24260, v36
	v_max_f32_e32 v35, 0xda24260, v35
	v_max_f32_e32 v37, 0xda24260, v37
	v_max_f32_e32 v38, 0xda24260, v139
	v_rcp_f32_e32 v34, v34
	v_rcp_f32_e32 v36, v36
	v_rcp_f32_e32 v35, v35
	v_rcp_f32_e32 v37, v37
	v_rcp_f32_e32 v139, v38
	v_pk_mul_f32 v[40:41], v[142:143], v[40:41]
	v_pk_mul_f32 v[38:39], v[148:149], v[34:35]
	v_pk_mul_f32 v[34:35], v[146:147], v[36:37]
	v_pk_mul_f32 v[36:37], v[144:145], v[138:139]
	s_mov_b64 s[0:1], 0

; __device__ __forceinline__ void unpack8(const u32x4 w, float (&f)[8]) { f[0] = bflo(w.x); f[1] = bfhi(w.x); f[2] = bflo(w.y); f[3] = bfhi(w.y); f[4] = bflo(w.z); f[5] = bfhi(w.z); f[6] = bflo(w.w); f[7] = bfhi(w.w); }
; __device__ __forceinline__ u32x4 pack8(const float (&f)[8]) { u32x4 w; w.x = cvt_pk_bf16(f[0], f[1]); w.y = cvt_pk_bf16(f[2], f[3]); w.z = cvt_pk_bf16(f[4], f[5]); w.w = cvt_pk_bf16(f[6], f[7]); return w; }
;     __device__ __forceinline__ void operator()(f32x4 (&acc)[2][2][4][2], const Unit& u, int wr, int wc, int fr, int fq) const {
;     ...
;             for (int m = 0; m < 4; ++m)
; #pragma unroll
;                 for (int bj = 0; bj < 2; ++bj) { const size_t row = (size_t)(row0 + ai * HALF + m * 16); const int col = col0 + bj * HALF;
;                     float gf[8], nf[8], v[8]; unpack8(gw[m][bj], gf); unpack8(gn[m][bj], nf);
; #pragma unroll
;                     for (int j = 0; j < 4; ++j) { v[j] = gf[j] * acc[ai][bj][m][0][j]; v[4 + j] = gf[4 + j] * acc[ai][bj][m][1][j]; }
;                     if (last) { *(u32x4*)(MG + row * 1024 + col) = pack8(v); acc[ai][bj][m][0] = (f32x4){0.f, 0.f, 0.f, 0.f}; acc[ai][bj][m][1] = (f32x4){0.f, 0.f, 0.f, 0.f}; }
;                     else {
; #pragma unroll
;                         for (int j = 0; j < 4; ++j) { acc[ai][bj][m][0][j] = v[j] * __builtin_amdgcn_rcpf(fmaxf(nf[j], 1e-30f)); acc[ai][bj][m][1][j] = v[4 + j] * __builtin_amdgcn_rcpf(fmaxf(nf[4 + j], 1e-30f)); } }
.LBB0_360:
	v_lshlrev_b32_e32 v6, 16, v131
	v_lshlrev_b32_e32 v9, 16, v133
	v_max_f32_e32 v6, 0xda24260, v6
	v_rcp_f32_e32 v8, v6
	v_and_b32_e32 v7, 0xffff0000, v131
	v_max_f32_e32 v6, 0xda24260, v9
	v_lshlrev_b32_e32 v2, 16, v130
	v_and_b32_e32 v3, 0xffff0000, v130
	v_rcp_f32_e32 v130, v6
	v_lshlrev_b32_e32 v4, 16, v132
	v_and_b32_e32 v5, 0xffff0000, v132
	v_and_b32_e32 v131, 0xffff0000, v133
	v_max_f32_e32 v6, 0xda24260, v7
	v_rcp_f32_e32 v9, v6
	v_max_f32_e32 v2, 0xda24260, v2
	v_max_f32_e32 v4, 0xda24260, v4
	v_max_f32_e32 v3, 0xda24260, v3
	v_max_f32_e32 v5, 0xda24260, v5
	v_max_f32_e32 v6, 0xda24260, v131
	v_rcp_f32_e32 v2, v2
	v_rcp_f32_e32 v4, v4
	v_rcp_f32_e32 v3, v3
	v_rcp_f32_e32 v5, v5
	v_rcp_f32_e32 v131, v6
	v_pk_mul_f32 v[8:9], v[134:135], v[8:9]
	v_pk_mul_f32 v[6:7], v[142:143], v[2:3]
	v_pk_mul_f32 v[2:3], v[140:141], v[4:5]
	v_pk_mul_f32 v[4:5], v[136:137], v[130:131]
	s_cbranch_execnz .LBB0_359
